# FFN gate/up epilogue: packed f32 multiplies/adds (v_pk_mul_f32/v_pk_add_f32) for the silu*u math, same operation order
# baseline (speedup 1.0000x reference)
; __device__ __forceinline__ float fast_silu(float z) { return z * __builtin_amdgcn_rcpf(1.f + __expf(-z)); }
;   __device__ __forceinline__ void operator()(f32x4 (&acc)[2][2][4][2], int brow, int bcol, int wr, int wc, int fr, int fq) const {
;     ...
; #pragma unroll
;     for (int ai = 0; ai < 2; ++ai)
; #pragma unroll
;       for (int m = 0; m < 4; ++m) {
;         int row0 = brow + ai * 128 + wr * 64 + m * 16 + fq * 4;
;         float rs[4];
; #pragma unroll
;         for (int j = 0; j < 4; ++j) rs[j] = rsqrtf(row16_sum(sv[ai][m][j]) * (1.f / 1024.f) + 1e-6f);
; #pragma unroll
;         for (int n = 0; n < 2; ++n) {
;           float a[4];
; #pragma unroll
;           for (int j = 0; j < 4; ++j) {
;             float g = acc[ai][0][m][n][j] * rs[j], u = acc[ai][1][m][n][j] * rs[j];
;             a[j] = fast_silu(g) * u;
;           }
;           store_rm4(act, 2816, row0, t * 128 + wc * 32 + n * 16 + fr, a[0], a[1], a[2], a[3], fr & 1);
;         }
;         __builtin_amdgcn_sched_barrier(0);
;       }
.Lmy_gu_have_rs:
	s_mov_b32 s98, 0xbfb8aa3b
	s_lshr_b32 s3, s33, 8
	v_lshrrev_b32_e32 v167, 4, v163
	v_and_b32_e32 v168, 1, v163
	s_lshl_b32 s4, s3, 8
	s_add_i32 s4, s4, 0x20010
	v_lshl_add_u32 v171, v167, 4, s4
	ds_read_b128 v[130:133], v171
	ds_read_b128 v[134:137], v171 offset:64
	ds_read_b128 v[138:141], v171 offset:128
	ds_read_b128 v[142:145], v171 offset:192
	ds_read_b128 v[146:149], v171 offset:512
	ds_read_b128 v[150:153], v171 offset:576
	ds_read_b128 v[154:157], v171 offset:640
	ds_read_b128 v[158:161], v171 offset:704
	s_ashr_i32 s0, s0, 1
	s_and_b32 s0, s0, 0xffffff80
	s_bfe_u32 s4, s33, 0x20006
	s_lshl_b32 s4, s4, 5
	s_add_i32 s0, s0, s4
	s_lshl_b32 s3, s3, 6
	s_add_i32 s3, s3, s2
	v_lshl_add_u32 v166, v167, 2, v168
	v_add_u32_e32 v166, s3, v166
	v_mul_u32_u24_e32 v166, 0x1600, v166
	v_and_b32_e32 v172, 14, v163
	v_add_u32_e32 v172, s0, v172
	v_lshl_add_u32 v166, v172, 1, v166
	v_mov_b32_e32 v164, 0x05040100
	v_mov_b32_e32 v173, 0x03020706
	v_cmp_eq_u32_e32 vcc, 1, v168
	s_nop 1
	v_cndmask_b32_e32 v164, v164, v173, vcc
	s_waitcnt lgkmcnt(0)
	v_mov_b32_e32 v169, v166
	v_add_u32_e32 v170, 0x2c00, v166
	v_pk_mul_f32 v[120:121], v[120:121], v[130:131]
	v_pk_mul_f32 v[122:123], v[122:123], v[132:133]
	v_pk_mul_f32 v[112:113], v[112:113], v[130:131]
	v_pk_mul_f32 v[114:115], v[114:115], v[132:133]
	v_pk_mul_f32 v[124:125], v[124:125], v[130:131]
	v_pk_mul_f32 v[126:127], v[126:127], v[132:133]
	v_pk_mul_f32 v[116:117], v[116:117], v[130:131]
	v_pk_mul_f32 v[118:119], v[118:119], v[132:133]
	v_pk_mul_f32 v[172:173], v[120:121], s[98:99] op_sel_hi:[1,0]
	v_pk_mul_f32 v[174:175], v[122:123], s[98:99] op_sel_hi:[1,0]
	v_pk_mul_f32 v[176:177], v[112:113], s[98:99] op_sel_hi:[1,0]
	v_pk_mul_f32 v[178:179], v[114:115], s[98:99] op_sel_hi:[1,0]
	v_exp_f32_e32 v172, v172
	v_exp_f32_e32 v173, v173
	v_exp_f32_e32 v174, v174
	v_exp_f32_e32 v175, v175
	v_exp_f32_e32 v176, v176
	v_exp_f32_e32 v177, v177
	v_exp_f32_e32 v178, v178
	v_exp_f32_e32 v179, v179
	v_pk_add_f32 v[172:173], v[172:173], 1.0 op_sel_hi:[1,0]
	v_pk_add_f32 v[174:175], v[174:175], 1.0 op_sel_hi:[1,0]
	v_pk_add_f32 v[176:177], v[176:177], 1.0 op_sel_hi:[1,0]
	v_pk_add_f32 v[178:179], v[178:179], 1.0 op_sel_hi:[1,0]
	v_rcp_f32_e32 v172, v172
	v_rcp_f32_e32 v173, v173
	v_rcp_f32_e32 v174, v174
	v_rcp_f32_e32 v175, v175
	v_rcp_f32_e32 v176, v176
	v_rcp_f32_e32 v177, v177
	v_rcp_f32_e32 v178, v178
	v_rcp_f32_e32 v179, v179
	v_pk_mul_f32 v[172:173], v[120:121], v[172:173]
	v_pk_mul_f32 v[174:175], v[122:123], v[174:175]
	v_pk_mul_f32 v[176:177], v[112:113], v[176:177]
	v_pk_mul_f32 v[178:179], v[114:115], v[178:179]
	v_pk_mul_f32 v[120:121], v[124:125], v[172:173]
	v_pk_mul_f32 v[122:123], v[126:127], v[174:175]
	v_pk_mul_f32 v[112:113], v[116:117], v[176:177]
	v_pk_mul_f32 v[114:115], v[118:119], v[178:179]
	v_cvt_pk_bf16_f32 v180, v120, v121
	v_cvt_pk_bf16_f32 v181, v122, v123
	v_cvt_pk_bf16_f32 v182, v112, v113
	v_cvt_pk_bf16_f32 v183, v114, v115
	v_mov_b32_dpp v184, v180 quad_perm:[1,0,3,2] row_mask:0xf bank_mask:0xf bound_ctrl:1
	v_mov_b32_dpp v185, v181 quad_perm:[1,0,3,2] row_mask:0xf bank_mask:0xf bound_ctrl:1
	v_mov_b32_dpp v186, v182 quad_perm:[1,0,3,2] row_mask:0xf bank_mask:0xf bound_ctrl:1
	v_mov_b32_dpp v187, v183 quad_perm:[1,0,3,2] row_mask:0xf bank_mask:0xf bound_ctrl:1
	v_perm_b32 v180, v184, v180, v164
	v_perm_b32 v181, v185, v181, v164
	v_perm_b32 v182, v186, v182, v164
	v_perm_b32 v183, v187, v183, v164
	global_store_dword v169, v180, s[34:35]
	global_store_dword v170, v181, s[34:35]
	global_store_dword v169, v182, s[34:35] offset:32
	global_store_dword v170, v183, s[34:35] offset:32
	v_add_u32_e32 v169, 0x16000, v166
	v_add_u32_e32 v170, 0x18c00, v166
	v_pk_mul_f32 v[104:105], v[104:105], v[134:135]
	v_pk_mul_f32 v[106:107], v[106:107], v[136:137]
	v_pk_mul_f32 v[96:97], v[96:97], v[134:135]
	v_pk_mul_f32 v[98:99], v[98:99], v[136:137]
	v_pk_mul_f32 v[108:109], v[108:109], v[134:135]
	v_pk_mul_f32 v[110:111], v[110:111], v[136:137]
	v_pk_mul_f32 v[100:101], v[100:101], v[134:135]
	v_pk_mul_f32 v[102:103], v[102:103], v[136:137]
	v_pk_mul_f32 v[172:173], v[104:105], s[98:99] op_sel_hi:[1,0]
	v_pk_mul_f32 v[174:175], v[106:107], s[98:99] op_sel_hi:[1,0]
	v_pk_mul_f32 v[176:177], v[96:97], s[98:99] op_sel_hi:[1,0]
	v_pk_mul_f32 v[178:179], v[98:99], s[98:99] op_sel_hi:[1,0]
	v_exp_f32_e32 v172, v172
	v_exp_f32_e32 v173, v173
	v_exp_f32_e32 v174, v174
	v_exp_f32_e32 v175, v175
	v_exp_f32_e32 v176, v176
	v_exp_f32_e32 v177, v177
	v_exp_f32_e32 v178, v178
	v_exp_f32_e32 v179, v179
	v_pk_add_f32 v[172:173], v[172:173], 1.0 op_sel_hi:[1,0]
	v_pk_add_f32 v[174:175], v[174:175], 1.0 op_sel_hi:[1,0]
	v_pk_add_f32 v[176:177], v[176:177], 1.0 op_sel_hi:[1,0]
	v_pk_add_f32 v[178:179], v[178:179], 1.0 op_sel_hi:[1,0]
	v_rcp_f32_e32 v172, v172
	v_rcp_f32_e32 v173, v173
	v_rcp_f32_e32 v174, v174
	v_rcp_f32_e32 v175, v175
	v_rcp_f32_e32 v176, v176
	v_rcp_f32_e32 v177, v177
	v_rcp_f32_e32 v178, v178
	v_rcp_f32_e32 v179, v179
	v_pk_mul_f32 v[172:173], v[104:105], v[172:173]
	v_pk_mul_f32 v[174:175], v[106:107], v[174:175]
	v_pk_mul_f32 v[176:177], v[96:97], v[176:177]
	v_pk_mul_f32 v[178:179], v[98:99], v[178:179]
	v_pk_mul_f32 v[104:105], v[108:109], v[172:173]
	v_pk_mul_f32 v[106:107], v[110:111], v[174:175]
	v_pk_mul_f32 v[96:97], v[100:101], v[176:177]
	v_pk_mul_f32 v[98:99], v[102:103], v[178:179]
	v_cvt_pk_bf16_f32 v180, v104, v105
	v_cvt_pk_bf16_f32 v181, v106, v107
	v_cvt_pk_bf16_f32 v182, v96, v97
	v_cvt_pk_bf16_f32 v183, v98, v99
	v_mov_b32_dpp v184, v180 quad_perm:[1,0,3,2] row_mask:0xf bank_mask:0xf bound_ctrl:1
	v_mov_b32_dpp v185, v181 quad_perm:[1,0,3,2] row_mask:0xf bank_mask:0xf bound_ctrl:1
; __device__ __forceinline__ float fast_silu(float z) { return z * __builtin_amdgcn_rcpf(1.f + __expf(-z)); }
;   __device__ __forceinline__ void operator()(f32x4 (&acc)[2][2][4][2], int brow, int bcol, int wr, int wc, int fr, int fq) const {
;     ...
; #pragma unroll
;     for (int ai = 0; ai < 2; ++ai)
; #pragma unroll
;       for (int m = 0; m < 4; ++m) {
;         int row0 = brow + ai * 128 + wr * 64 + m * 16 + fq * 4;
;         float rs[4];
; #pragma unroll
;         for (int j = 0; j < 4; ++j) rs[j] = rsqrtf(row16_sum(sv[ai][m][j]) * (1.f / 1024.f) + 1e-6f);
; #pragma unroll
;         for (int n = 0; n < 2; ++n) {
;           float a[4];
; #pragma unroll
;           for (int j = 0; j < 4; ++j) {
;             float g = acc[ai][0][m][n][j] * rs[j], u = acc[ai][1][m][n][j] * rs[j];
;             a[j] = fast_silu(g) * u;
;           }
;           store_rm4(act, 2816, row0, t * 128 + wc * 32 + n * 16 + fr, a[0], a[1], a[2], a[3], fr & 1);
;         }
;         __builtin_amdgcn_sched_barrier(0);
;       }
	v_mov_b32_dpp v186, v182 quad_perm:[1,0,3,2] row_mask:0xf bank_mask:0xf bound_ctrl:1
	v_mov_b32_dpp v187, v183 quad_perm:[1,0,3,2] row_mask:0xf bank_mask:0xf bound_ctrl:1
	v_perm_b32 v180, v184, v180, v164
	v_perm_b32 v181, v185, v181, v164
	v_perm_b32 v182, v186, v182, v164
	v_perm_b32 v183, v187, v183, v164
	global_store_dword v169, v180, s[34:35]
	global_store_dword v170, v181, s[34:35]
	global_store_dword v169, v182, s[34:35] offset:32
	global_store_dword v170, v183, s[34:35] offset:32
	v_add_u32_e32 v169, 0x2c000, v166
	v_add_u32_e32 v170, 0x2ec00, v166
	v_pk_mul_f32 v[88:89], v[88:89], v[138:139]
	v_pk_mul_f32 v[90:91], v[90:91], v[140:141]
	v_pk_mul_f32 v[80:81], v[80:81], v[138:139]
	v_pk_mul_f32 v[82:83], v[82:83], v[140:141]
	v_pk_mul_f32 v[92:93], v[92:93], v[138:139]
	v_pk_mul_f32 v[94:95], v[94:95], v[140:141]
	v_pk_mul_f32 v[84:85], v[84:85], v[138:139]
	v_pk_mul_f32 v[86:87], v[86:87], v[140:141]
	v_pk_mul_f32 v[172:173], v[88:89], s[98:99] op_sel_hi:[1,0]
	v_pk_mul_f32 v[174:175], v[90:91], s[98:99] op_sel_hi:[1,0]
	v_pk_mul_f32 v[176:177], v[80:81], s[98:99] op_sel_hi:[1,0]
	v_pk_mul_f32 v[178:179], v[82:83], s[98:99] op_sel_hi:[1,0]
	v_exp_f32_e32 v172, v172
	v_exp_f32_e32 v173, v173
	v_exp_f32_e32 v174, v174
	v_exp_f32_e32 v175, v175
	v_exp_f32_e32 v176, v176
	v_exp_f32_e32 v177, v177
	v_exp_f32_e32 v178, v178
	v_exp_f32_e32 v179, v179
	v_pk_add_f32 v[172:173], v[172:173], 1.0 op_sel_hi:[1,0]
	v_pk_add_f32 v[174:175], v[174:175], 1.0 op_sel_hi:[1,0]
	v_pk_add_f32 v[176:177], v[176:177], 1.0 op_sel_hi:[1,0]
	v_pk_add_f32 v[178:179], v[178:179], 1.0 op_sel_hi:[1,0]
	v_rcp_f32_e32 v172, v172
	v_rcp_f32_e32 v173, v173
	v_rcp_f32_e32 v174, v174
	v_rcp_f32_e32 v175, v175
	v_rcp_f32_e32 v176, v176
	v_rcp_f32_e32 v177, v177
	v_rcp_f32_e32 v178, v178
	v_rcp_f32_e32 v179, v179
	v_pk_mul_f32 v[172:173], v[88:89], v[172:173]
	v_pk_mul_f32 v[174:175], v[90:91], v[174:175]
	v_pk_mul_f32 v[176:177], v[80:81], v[176:177]
	v_pk_mul_f32 v[178:179], v[82:83], v[178:179]
	v_pk_mul_f32 v[88:89], v[92:93], v[172:173]
	v_pk_mul_f32 v[90:91], v[94:95], v[174:175]
	v_pk_mul_f32 v[80:81], v[84:85], v[176:177]
	v_pk_mul_f32 v[82:83], v[86:87], v[178:179]
	v_cvt_pk_bf16_f32 v180, v88, v89
	v_cvt_pk_bf16_f32 v181, v90, v91
	v_cvt_pk_bf16_f32 v182, v80, v81
	v_cvt_pk_bf16_f32 v183, v82, v83
	v_mov_b32_dpp v184, v180 quad_perm:[1,0,3,2] row_mask:0xf bank_mask:0xf bound_ctrl:1
	v_mov_b32_dpp v185, v181 quad_perm:[1,0,3,2] row_mask:0xf bank_mask:0xf bound_ctrl:1
	v_mov_b32_dpp v186, v182 quad_perm:[1,0,3,2] row_mask:0xf bank_mask:0xf bound_ctrl:1
	v_mov_b32_dpp v187, v183 quad_perm:[1,0,3,2] row_mask:0xf bank_mask:0xf bound_ctrl:1
	v_perm_b32 v180, v184, v180, v164
	v_perm_b32 v181, v185, v181, v164
	v_perm_b32 v182, v186, v182, v164
	v_perm_b32 v183, v187, v183, v164
	global_store_dword v169, v180, s[34:35]
	global_store_dword v170, v181, s[34:35]
	global_store_dword v169, v182, s[34:35] offset:32
	global_store_dword v170, v183, s[34:35] offset:32
	v_add_u32_e32 v169, 0x42000, v166
	v_add_u32_e32 v170, 0x44c00, v166
	v_pk_mul_f32 v[72:73], v[72:73], v[142:143]
	v_pk_mul_f32 v[74:75], v[74:75], v[144:145]
	v_pk_mul_f32 v[64:65], v[64:65], v[142:143]
	v_pk_mul_f32 v[66:67], v[66:67], v[144:145]
	v_pk_mul_f32 v[76:77], v[76:77], v[142:143]
	v_pk_mul_f32 v[78:79], v[78:79], v[144:145]
	v_pk_mul_f32 v[68:69], v[68:69], v[142:143]
	v_pk_mul_f32 v[70:71], v[70:71], v[144:145]
	v_pk_mul_f32 v[172:173], v[72:73], s[98:99] op_sel_hi:[1,0]
	v_pk_mul_f32 v[174:175], v[74:75], s[98:99] op_sel_hi:[1,0]
	v_pk_mul_f32 v[176:177], v[64:65], s[98:99] op_sel_hi:[1,0]
	v_pk_mul_f32 v[178:179], v[66:67], s[98:99] op_sel_hi:[1,0]
	v_exp_f32_e32 v172, v172
	v_exp_f32_e32 v173, v173
	v_exp_f32_e32 v174, v174
	v_exp_f32_e32 v175, v175
	v_exp_f32_e32 v176, v176
	v_exp_f32_e32 v177, v177
	v_exp_f32_e32 v178, v178
	v_exp_f32_e32 v179, v179
	v_pk_add_f32 v[172:173], v[172:173], 1.0 op_sel_hi:[1,0]
	v_pk_add_f32 v[174:175], v[174:175], 1.0 op_sel_hi:[1,0]
	v_pk_add_f32 v[176:177], v[176:177], 1.0 op_sel_hi:[1,0]
	v_pk_add_f32 v[178:179], v[178:179], 1.0 op_sel_hi:[1,0]
	v_rcp_f32_e32 v172, v172
	v_rcp_f32_e32 v173, v173
	v_rcp_f32_e32 v174, v174
	v_rcp_f32_e32 v175, v175
	v_rcp_f32_e32 v176, v176
	v_rcp_f32_e32 v177, v177
	v_rcp_f32_e32 v178, v178
	v_rcp_f32_e32 v179, v179
	v_pk_mul_f32 v[172:173], v[72:73], v[172:173]
	v_pk_mul_f32 v[174:175], v[74:75], v[174:175]
	v_pk_mul_f32 v[176:177], v[64:65], v[176:177]
	v_pk_mul_f32 v[178:179], v[66:67], v[178:179]
	v_pk_mul_f32 v[72:73], v[76:77], v[172:173]
	v_pk_mul_f32 v[74:75], v[78:79], v[174:175]
	v_pk_mul_f32 v[64:65], v[68:69], v[176:177]
	v_pk_mul_f32 v[66:67], v[70:71], v[178:179]
	v_cvt_pk_bf16_f32 v180, v72, v73
	v_cvt_pk_bf16_f32 v181, v74, v75
	v_cvt_pk_bf16_f32 v182, v64, v65
	v_cvt_pk_bf16_f32 v183, v66, v67
	v_mov_b32_dpp v184, v180 quad_perm:[1,0,3,2] row_mask:0xf bank_mask:0xf bound_ctrl:1
	v_mov_b32_dpp v185, v181 quad_perm:[1,0,3,2] row_mask:0xf bank_mask:0xf bound_ctrl:1
	v_mov_b32_dpp v186, v182 quad_perm:[1,0,3,2] row_mask:0xf bank_mask:0xf bound_ctrl:1
	v_mov_b32_dpp v187, v183 quad_perm:[1,0,3,2] row_mask:0xf bank_mask:0xf bound_ctrl:1
	v_perm_b32 v180, v184, v180, v164
	v_perm_b32 v181, v185, v181, v164
	v_perm_b32 v182, v186, v182, v164
	v_perm_b32 v183, v187, v183, v164
	global_store_dword v169, v180, s[34:35]
	global_store_dword v170, v181, s[34:35]
	global_store_dword v169, v182, s[34:35] offset:32
	global_store_dword v170, v183, s[34:35] offset:32
	v_add_u32_e32 v169, 0xb0000, v166
	v_add_u32_e32 v170, 0xb2c00, v166
	v_pk_mul_f32 v[56:57], v[56:57], v[146:147]
	v_pk_mul_f32 v[58:59], v[58:59], v[148:149]
; __device__ __forceinline__ float fast_silu(float z) { return z * __builtin_amdgcn_rcpf(1.f + __expf(-z)); }
;   __device__ __forceinline__ void operator()(f32x4 (&acc)[2][2][4][2], int brow, int bcol, int wr, int wc, int fr, int fq) const {
;     ...
; #pragma unroll
;     for (int ai = 0; ai < 2; ++ai)
; #pragma unroll
;       for (int m = 0; m < 4; ++m) {
;         int row0 = brow + ai * 128 + wr * 64 + m * 16 + fq * 4;
;         float rs[4];
; #pragma unroll
;         for (int j = 0; j < 4; ++j) rs[j] = rsqrtf(row16_sum(sv[ai][m][j]) * (1.f / 1024.f) + 1e-6f);
; #pragma unroll
;         for (int n = 0; n < 2; ++n) {
;           float a[4];
; #pragma unroll
;           for (int j = 0; j < 4; ++j) {
;             float g = acc[ai][0][m][n][j] * rs[j], u = acc[ai][1][m][n][j] * rs[j];
;             a[j] = fast_silu(g) * u;
;           }
;           store_rm4(act, 2816, row0, t * 128 + wc * 32 + n * 16 + fr, a[0], a[1], a[2], a[3], fr & 1);
;         }
;         __builtin_amdgcn_sched_barrier(0);
;       }
	v_pk_mul_f32 v[48:49], v[48:49], v[146:147]
	v_pk_mul_f32 v[50:51], v[50:51], v[148:149]
	v_pk_mul_f32 v[60:61], v[60:61], v[146:147]
	v_pk_mul_f32 v[62:63], v[62:63], v[148:149]
	v_pk_mul_f32 v[52:53], v[52:53], v[146:147]
	v_pk_mul_f32 v[54:55], v[54:55], v[148:149]
	v_pk_mul_f32 v[172:173], v[56:57], s[98:99] op_sel_hi:[1,0]
	v_pk_mul_f32 v[174:175], v[58:59], s[98:99] op_sel_hi:[1,0]
	v_pk_mul_f32 v[176:177], v[48:49], s[98:99] op_sel_hi:[1,0]
	v_pk_mul_f32 v[178:179], v[50:51], s[98:99] op_sel_hi:[1,0]
	v_exp_f32_e32 v172, v172
	v_exp_f32_e32 v173, v173
	v_exp_f32_e32 v174, v174
	v_exp_f32_e32 v175, v175
	v_exp_f32_e32 v176, v176
	v_exp_f32_e32 v177, v177
	v_exp_f32_e32 v178, v178
	v_exp_f32_e32 v179, v179
	v_pk_add_f32 v[172:173], v[172:173], 1.0 op_sel_hi:[1,0]
	v_pk_add_f32 v[174:175], v[174:175], 1.0 op_sel_hi:[1,0]
	v_pk_add_f32 v[176:177], v[176:177], 1.0 op_sel_hi:[1,0]
	v_pk_add_f32 v[178:179], v[178:179], 1.0 op_sel_hi:[1,0]
	v_rcp_f32_e32 v172, v172
	v_rcp_f32_e32 v173, v173
	v_rcp_f32_e32 v174, v174
	v_rcp_f32_e32 v175, v175
	v_rcp_f32_e32 v176, v176
	v_rcp_f32_e32 v177, v177
	v_rcp_f32_e32 v178, v178
	v_rcp_f32_e32 v179, v179
	v_pk_mul_f32 v[172:173], v[56:57], v[172:173]
	v_pk_mul_f32 v[174:175], v[58:59], v[174:175]
	v_pk_mul_f32 v[176:177], v[48:49], v[176:177]
	v_pk_mul_f32 v[178:179], v[50:51], v[178:179]
	v_pk_mul_f32 v[56:57], v[60:61], v[172:173]
	v_pk_mul_f32 v[58:59], v[62:63], v[174:175]
	v_pk_mul_f32 v[48:49], v[52:53], v[176:177]
	v_pk_mul_f32 v[50:51], v[54:55], v[178:179]
	v_cvt_pk_bf16_f32 v180, v56, v57
	v_cvt_pk_bf16_f32 v181, v58, v59
	v_cvt_pk_bf16_f32 v182, v48, v49
	v_cvt_pk_bf16_f32 v183, v50, v51
	v_mov_b32_dpp v184, v180 quad_perm:[1,0,3,2] row_mask:0xf bank_mask:0xf bound_ctrl:1
	v_mov_b32_dpp v185, v181 quad_perm:[1,0,3,2] row_mask:0xf bank_mask:0xf bound_ctrl:1
	v_mov_b32_dpp v186, v182 quad_perm:[1,0,3,2] row_mask:0xf bank_mask:0xf bound_ctrl:1
	v_mov_b32_dpp v187, v183 quad_perm:[1,0,3,2] row_mask:0xf bank_mask:0xf bound_ctrl:1
	v_perm_b32 v180, v184, v180, v164
	v_perm_b32 v181, v185, v181, v164
	v_perm_b32 v182, v186, v182, v164
	v_perm_b32 v183, v187, v183, v164
	global_store_dword v169, v180, s[34:35]
	global_store_dword v170, v181, s[34:35]
	global_store_dword v169, v182, s[34:35] offset:32
	global_store_dword v170, v183, s[34:35] offset:32
	v_add_u32_e32 v169, 0xc6000, v166
	v_add_u32_e32 v170, 0xc8c00, v166
	v_pk_mul_f32 v[40:41], v[40:41], v[150:151]
	v_pk_mul_f32 v[42:43], v[42:43], v[152:153]
	v_pk_mul_f32 v[32:33], v[32:33], v[150:151]
	v_pk_mul_f32 v[34:35], v[34:35], v[152:153]
	v_pk_mul_f32 v[44:45], v[44:45], v[150:151]
	v_pk_mul_f32 v[46:47], v[46:47], v[152:153]
	v_pk_mul_f32 v[36:37], v[36:37], v[150:151]
	v_pk_mul_f32 v[38:39], v[38:39], v[152:153]
	v_pk_mul_f32 v[172:173], v[40:41], s[98:99] op_sel_hi:[1,0]
	v_pk_mul_f32 v[174:175], v[42:43], s[98:99] op_sel_hi:[1,0]
	v_pk_mul_f32 v[176:177], v[32:33], s[98:99] op_sel_hi:[1,0]
	v_pk_mul_f32 v[178:179], v[34:35], s[98:99] op_sel_hi:[1,0]
	v_exp_f32_e32 v172, v172
	v_exp_f32_e32 v173, v173
	v_exp_f32_e32 v174, v174
	v_exp_f32_e32 v175, v175
	v_exp_f32_e32 v176, v176
	v_exp_f32_e32 v177, v177
	v_exp_f32_e32 v178, v178
	v_exp_f32_e32 v179, v179
	v_pk_add_f32 v[172:173], v[172:173], 1.0 op_sel_hi:[1,0]
	v_pk_add_f32 v[174:175], v[174:175], 1.0 op_sel_hi:[1,0]
	v_pk_add_f32 v[176:177], v[176:177], 1.0 op_sel_hi:[1,0]
	v_pk_add_f32 v[178:179], v[178:179], 1.0 op_sel_hi:[1,0]
	v_rcp_f32_e32 v172, v172
	v_rcp_f32_e32 v173, v173
	v_rcp_f32_e32 v174, v174
	v_rcp_f32_e32 v175, v175
	v_rcp_f32_e32 v176, v176
	v_rcp_f32_e32 v177, v177
	v_rcp_f32_e32 v178, v178
	v_rcp_f32_e32 v179, v179
	v_pk_mul_f32 v[172:173], v[40:41], v[172:173]
	v_pk_mul_f32 v[174:175], v[42:43], v[174:175]
	v_pk_mul_f32 v[176:177], v[32:33], v[176:177]
	v_pk_mul_f32 v[178:179], v[34:35], v[178:179]
	v_pk_mul_f32 v[40:41], v[44:45], v[172:173]
	v_pk_mul_f32 v[42:43], v[46:47], v[174:175]
	v_pk_mul_f32 v[32:33], v[36:37], v[176:177]
	v_pk_mul_f32 v[34:35], v[38:39], v[178:179]
	v_cvt_pk_bf16_f32 v180, v40, v41
	v_cvt_pk_bf16_f32 v181, v42, v43
	v_cvt_pk_bf16_f32 v182, v32, v33
	v_cvt_pk_bf16_f32 v183, v34, v35
	v_mov_b32_dpp v184, v180 quad_perm:[1,0,3,2] row_mask:0xf bank_mask:0xf bound_ctrl:1
	v_mov_b32_dpp v185, v181 quad_perm:[1,0,3,2] row_mask:0xf bank_mask:0xf bound_ctrl:1
	v_mov_b32_dpp v186, v182 quad_perm:[1,0,3,2] row_mask:0xf bank_mask:0xf bound_ctrl:1
	v_mov_b32_dpp v187, v183 quad_perm:[1,0,3,2] row_mask:0xf bank_mask:0xf bound_ctrl:1
	v_perm_b32 v180, v184, v180, v164
	v_perm_b32 v181, v185, v181, v164
	v_perm_b32 v182, v186, v182, v164
	v_perm_b32 v183, v187, v183, v164
	global_store_dword v169, v180, s[34:35]
	global_store_dword v170, v181, s[34:35]
	global_store_dword v169, v182, s[34:35] offset:32
	global_store_dword v170, v183, s[34:35] offset:32
	v_add_u32_e32 v169, 0xdc000, v166
	v_add_u32_e32 v170, 0xdec00, v166
	v_pk_mul_f32 v[24:25], v[24:25], v[154:155]
; __device__ __forceinline__ float fast_silu(float z) { return z * __builtin_amdgcn_rcpf(1.f + __expf(-z)); }
; #define WAIT_L(n) asm volatile("s_waitcnt lgkmcnt(" #n ")" ::: "memory")
; #define BAR __builtin_amdgcn_s_barrier()
; template <class Epi>
; __device__ __forceinline__ void gemm_tile(const u16* __restrict__ A, const u16* __restrict__ Bt, int K,
;                                           int brow, int bcol, bool first, bool has_next, int nbrow, int nbcol, Epi epi) {
;     ...
;   WAIT_L(0); BAR;
; template <class Epi>
; __device__ __forceinline__ void gemm_phase(const u16* A, const u16* Bt, int K, int nN, Epi epi) {
;     ...
;     for (int rd = 0; rd < nN; ++rd) {
;       int nbrow = 0, nbcol = 0;
;       bool has_next = rd + 1 < nN;
;       if (has_next) {
;         int l2 = (rd + 1) * 32 + j;
;         int mg2 = l2 / (nN * 8), rem2 = l2 % (nN * 8);
;         nbrow = (x * 32 + mg2 * 8 + (rem2 & 7)) * 256; nbcol = (rem2 >> 3) * 256;
;       }
;       gemm_tile(A, Bt, K, brow, bcol, rd == 0, has_next, nbrow, nbcol, epi);
;       brow = nbrow; bcol = nbcol;
;     }
;   __device__ __forceinline__ void operator()(f32x4 (&acc)[2][2][4][2], int brow, int bcol, int wr, int wc, int fr, int fq) const {
;     ...
; #pragma unroll
;     for (int ai = 0; ai < 2; ++ai)
; #pragma unroll
;       for (int m = 0; m < 4; ++m) {
;         int row0 = brow + ai * 128 + wr * 64 + m * 16 + fq * 4;
;         float rs[4];
; #pragma unroll
;         for (int j = 0; j < 4; ++j) rs[j] = rsqrtf(row16_sum(sv[ai][m][j]) * (1.f / 1024.f) + 1e-6f);
; #pragma unroll
;         for (int n = 0; n < 2; ++n) {
;           float a[4];
; #pragma unroll
;           for (int j = 0; j < 4; ++j) {
;             float g = acc[ai][0][m][n][j] * rs[j], u = acc[ai][1][m][n][j] * rs[j];
;             a[j] = fast_silu(g) * u;
;           }
;           store_rm4(act, 2816, row0, t * 128 + wc * 32 + n * 16 + fr, a[0], a[1], a[2], a[3], fr & 1);
;         }
;         __builtin_amdgcn_sched_barrier(0);
;       }
	v_pk_mul_f32 v[26:27], v[26:27], v[156:157]
	v_pk_mul_f32 v[16:17], v[16:17], v[154:155]
	v_pk_mul_f32 v[18:19], v[18:19], v[156:157]
	v_pk_mul_f32 v[28:29], v[28:29], v[154:155]
	v_pk_mul_f32 v[30:31], v[30:31], v[156:157]
	v_pk_mul_f32 v[20:21], v[20:21], v[154:155]
	v_pk_mul_f32 v[22:23], v[22:23], v[156:157]
	v_pk_mul_f32 v[172:173], v[24:25], s[98:99] op_sel_hi:[1,0]
	v_pk_mul_f32 v[174:175], v[26:27], s[98:99] op_sel_hi:[1,0]
	v_pk_mul_f32 v[176:177], v[16:17], s[98:99] op_sel_hi:[1,0]
	v_pk_mul_f32 v[178:179], v[18:19], s[98:99] op_sel_hi:[1,0]
	v_exp_f32_e32 v172, v172
	v_exp_f32_e32 v173, v173
	v_exp_f32_e32 v174, v174
	v_exp_f32_e32 v175, v175
	v_exp_f32_e32 v176, v176
	v_exp_f32_e32 v177, v177
	v_exp_f32_e32 v178, v178
	v_exp_f32_e32 v179, v179
	v_pk_add_f32 v[172:173], v[172:173], 1.0 op_sel_hi:[1,0]
	v_pk_add_f32 v[174:175], v[174:175], 1.0 op_sel_hi:[1,0]
	v_pk_add_f32 v[176:177], v[176:177], 1.0 op_sel_hi:[1,0]
	v_pk_add_f32 v[178:179], v[178:179], 1.0 op_sel_hi:[1,0]
	v_rcp_f32_e32 v172, v172
	v_rcp_f32_e32 v173, v173
	v_rcp_f32_e32 v174, v174
	v_rcp_f32_e32 v175, v175
	v_rcp_f32_e32 v176, v176
	v_rcp_f32_e32 v177, v177
	v_rcp_f32_e32 v178, v178
	v_rcp_f32_e32 v179, v179
	v_pk_mul_f32 v[172:173], v[24:25], v[172:173]
	v_pk_mul_f32 v[174:175], v[26:27], v[174:175]
	v_pk_mul_f32 v[176:177], v[16:17], v[176:177]
	v_pk_mul_f32 v[178:179], v[18:19], v[178:179]
	v_pk_mul_f32 v[24:25], v[28:29], v[172:173]
	v_pk_mul_f32 v[26:27], v[30:31], v[174:175]
	v_pk_mul_f32 v[16:17], v[20:21], v[176:177]
	v_pk_mul_f32 v[18:19], v[22:23], v[178:179]
	v_cvt_pk_bf16_f32 v180, v24, v25
	v_cvt_pk_bf16_f32 v181, v26, v27
	v_cvt_pk_bf16_f32 v182, v16, v17
	v_cvt_pk_bf16_f32 v183, v18, v19
	v_mov_b32_dpp v184, v180 quad_perm:[1,0,3,2] row_mask:0xf bank_mask:0xf bound_ctrl:1
	v_mov_b32_dpp v185, v181 quad_perm:[1,0,3,2] row_mask:0xf bank_mask:0xf bound_ctrl:1
	v_mov_b32_dpp v186, v182 quad_perm:[1,0,3,2] row_mask:0xf bank_mask:0xf bound_ctrl:1
	v_mov_b32_dpp v187, v183 quad_perm:[1,0,3,2] row_mask:0xf bank_mask:0xf bound_ctrl:1
	v_perm_b32 v180, v184, v180, v164
	v_perm_b32 v181, v185, v181, v164
	v_perm_b32 v182, v186, v182, v164
	v_perm_b32 v183, v187, v183, v164
	global_store_dword v169, v180, s[34:35]
	global_store_dword v170, v181, s[34:35]
	global_store_dword v169, v182, s[34:35] offset:32
	global_store_dword v170, v183, s[34:35] offset:32
	v_add_u32_e32 v169, 0xf2000, v166
	v_add_u32_e32 v170, 0xf4c00, v166
	v_pk_mul_f32 v[8:9], v[8:9], v[158:159]
	v_pk_mul_f32 v[10:11], v[10:11], v[160:161]
	v_pk_mul_f32 v[0:1], v[0:1], v[158:159]
	v_pk_mul_f32 v[2:3], v[2:3], v[160:161]
	v_pk_mul_f32 v[12:13], v[12:13], v[158:159]
	v_pk_mul_f32 v[14:15], v[14:15], v[160:161]
	v_pk_mul_f32 v[4:5], v[4:5], v[158:159]
	v_pk_mul_f32 v[6:7], v[6:7], v[160:161]
	v_pk_mul_f32 v[172:173], v[8:9], s[98:99] op_sel_hi:[1,0]
	v_pk_mul_f32 v[174:175], v[10:11], s[98:99] op_sel_hi:[1,0]
	v_pk_mul_f32 v[176:177], v[0:1], s[98:99] op_sel_hi:[1,0]
	v_pk_mul_f32 v[178:179], v[2:3], s[98:99] op_sel_hi:[1,0]
	v_exp_f32_e32 v172, v172
	v_exp_f32_e32 v173, v173
	v_exp_f32_e32 v174, v174
	v_exp_f32_e32 v175, v175
	v_exp_f32_e32 v176, v176
	v_exp_f32_e32 v177, v177
	v_exp_f32_e32 v178, v178
	v_exp_f32_e32 v179, v179
	v_pk_add_f32 v[172:173], v[172:173], 1.0 op_sel_hi:[1,0]
	v_pk_add_f32 v[174:175], v[174:175], 1.0 op_sel_hi:[1,0]
	v_pk_add_f32 v[176:177], v[176:177], 1.0 op_sel_hi:[1,0]
	v_pk_add_f32 v[178:179], v[178:179], 1.0 op_sel_hi:[1,0]
	v_rcp_f32_e32 v172, v172
	v_rcp_f32_e32 v173, v173
	v_rcp_f32_e32 v174, v174
	v_rcp_f32_e32 v175, v175
	v_rcp_f32_e32 v176, v176
	v_rcp_f32_e32 v177, v177
	v_rcp_f32_e32 v178, v178
	v_rcp_f32_e32 v179, v179
	v_pk_mul_f32 v[172:173], v[8:9], v[172:173]
	v_pk_mul_f32 v[174:175], v[10:11], v[174:175]
	v_pk_mul_f32 v[176:177], v[0:1], v[176:177]
	v_pk_mul_f32 v[178:179], v[2:3], v[178:179]
	v_pk_mul_f32 v[8:9], v[12:13], v[172:173]
	v_pk_mul_f32 v[10:11], v[14:15], v[174:175]
	v_pk_mul_f32 v[0:1], v[4:5], v[176:177]
	v_pk_mul_f32 v[2:3], v[6:7], v[178:179]
	v_cvt_pk_bf16_f32 v180, v8, v9
	v_cvt_pk_bf16_f32 v181, v10, v11
	v_cvt_pk_bf16_f32 v182, v0, v1
	v_cvt_pk_bf16_f32 v183, v2, v3
	v_mov_b32_dpp v184, v180 quad_perm:[1,0,3,2] row_mask:0xf bank_mask:0xf bound_ctrl:1
	v_mov_b32_dpp v185, v181 quad_perm:[1,0,3,2] row_mask:0xf bank_mask:0xf bound_ctrl:1
	v_mov_b32_dpp v186, v182 quad_perm:[1,0,3,2] row_mask:0xf bank_mask:0xf bound_ctrl:1
	v_mov_b32_dpp v187, v183 quad_perm:[1,0,3,2] row_mask:0xf bank_mask:0xf bound_ctrl:1
	v_perm_b32 v180, v184, v180, v164
	v_perm_b32 v181, v185, v181, v164
	v_perm_b32 v182, v186, v182, v164
	v_perm_b32 v183, v187, v183, v164
	global_store_dword v169, v180, s[34:35]
	global_store_dword v170, v181, s[34:35]
	global_store_dword v169, v182, s[34:35] offset:32
	global_store_dword v170, v183, s[34:35] offset:32
	s_waitcnt lgkmcnt(0)
	s_cmp_lg_u32 s64, 22
	s_mov_b32 s2, s30
	s_mov_b32 s0, s28
	s_mov_b32 s1, s64
	s_barrier
	s_cbranch_scc0 .LBB0_597
